# p3a S3: all sixteen MFMA fragment reads issued up front with counted waits; beta and gcum quads of the four row groups of each LT epilogue fetched in one batch instead of one LDS round trip per group
# speedup vs baseline: 1.0149x; 1.0003x over previous
.LBB0_615:
	s_mov_b64 s[4:5], -1
	s_andn2_b64 vcc, exec, s[28:29]
	v_lshlrev_b32_e32 v19, 4, v160
	s_waitcnt lgkmcnt(0)
	s_barrier
	s_cbranch_vccnz .LBB0_641
	v_and_b32_e32 v102, 31, v160
	v_ashrrev_i32_e32 v2, 3, v160
	v_and_b32_e32 v20, 0xfffffe0, v160
	v_and_b32_e32 v21, -4, v2
	v_bitop3_b32 v2, v2, v102, -4 bitop3:0x6c
	v_add_lshl_u32 v6, v2, v20, 4
	v_readlane_b32 s4, v248, 11
	v_readlane_b32 s5, v248, 13
	v_add_u32_e32 v98, 8, v21
	v_add_u32_e32 v103, s4, v6
	v_add_u32_e32 v108, s5, v19
	v_readlane_b32 s5, v248, 12
	v_add_u32_e32 v7, 0x4000, v108
	v_bitop3_b32 v98, v98, v160, 31 bitop3:0x78
	v_add_u32_e32 v109, s5, v6
	v_add_lshl_u32 v20, v98, v20, 4
	v_add_u32_e32 v110, s4, v20
	v_add_u32_e32 v20, s5, v20
	v_cndmask_b32_e64 v104, v109, v7, s[20:21]
	v_cndmask_b32_e64 v105, v20, v7, s[20:21]
	ds_read_b128 v[2:5], v103
	ds_read_b128 v[6:9], v104
	ds_read_b128 v[112:115], v110 offset:1024
	ds_read_b128 v[116:119], v105 offset:1024
	ds_read_b128 v[120:123], v103 offset:2048
	ds_read_b128 v[124:127], v104 offset:2048
	ds_read_b128 v[128:131], v110 offset:3072
	ds_read_b128 v[132:135], v105 offset:3072
	ds_read_b128 v[136:139], v103 offset:4096
	ds_read_b128 v[140:143], v104 offset:4096
	ds_read_b128 v[144:147], v110 offset:5120
	ds_read_b128 v[148:151], v105 offset:5120
	ds_read_b128 v[152:155], v103 offset:6144
	ds_read_b128 v[232:235], v104 offset:6144
	ds_read_b128 v[228:231], v110 offset:7168
	ds_read_b128 v[236:239], v105 offset:7168
	v_readlane_b32 s5, v249, 60
	s_movk_i32 s4, 0xc0
	s_mov_b64 s[8:9], -1
	s_waitcnt lgkmcnt(14)
	v_mfma_f32_32x32x16_bf16 v[2:17], v[2:5], v[6:9], 0
	s_lshl_b32 s40, s5, 2
	s_waitcnt lgkmcnt(12)
	v_mfma_f32_32x32x16_bf16 v[2:17], v[112:115], v[116:119], v[2:17]
	s_waitcnt lgkmcnt(10)
	v_mfma_f32_32x32x16_bf16 v[2:17], v[120:123], v[124:127], v[2:17]
	s_waitcnt lgkmcnt(8)
	v_mfma_f32_32x32x16_bf16 v[2:17], v[128:131], v[132:135], v[2:17]
	s_waitcnt lgkmcnt(6)
	v_mfma_f32_32x32x16_bf16 v[2:17], v[136:139], v[140:143], v[2:17]
	s_waitcnt lgkmcnt(4)
	v_mfma_f32_32x32x16_bf16 v[2:17], v[144:147], v[148:151], v[2:17]
	s_waitcnt lgkmcnt(2)
	v_mfma_f32_32x32x16_bf16 v[2:17], v[152:155], v[232:235], v[2:17]
	s_waitcnt lgkmcnt(0)
	v_mfma_f32_32x32x16_bf16 v[2:17], v[228:231], v[236:239], v[2:17]
	v_or_b32_e32 v100, s5, v102
	v_add_u32_e32 v20, 1, v100
	v_lshrrev_b32_e32 v98, 2, v20
	v_and_b32_e32 v103, 0x7c, v20
	v_add_u32_e32 v99, -1, v98
	v_mul_i32_i24_e32 v98, -8, v98
	v_lshlrev_b32_e32 v101, 8, v99
	v_mul_lo_u32 v98, v98, v99
	v_and_b32_e32 v20, 3, v20
	v_sub_u32_e32 v99, 64, v103
	v_mad_u32_u24 v20, v99, v20, v101
	v_add3_u32 v20, v20, v98, s4
	v_readlane_b32 s4, v249, 61
	v_cmp_gt_u32_e64 s[6:7], 3, v100
	v_lshlrev_b32_e32 v98, 6, v102
	v_add_u32_e32 v101, s4, v21
	s_lshl_b32 s4, s64, 9
	s_add_i32 s46, s4, 0
	s_add_i32 s46, s46, 0x21000
	s_add_i32 s4, s46, s40
	v_lshl_add_u32 v21, v102, 2, s4
	ds_read_b32 v117, v21
	v_readlane_b32 s4, v249, 58
	v_sub_u32_e32 v99, 0, v103
	v_readlane_b32 s5, v249, 59
	s_and_b64 vcc, exec, s[4:5]
	v_lshlrev_b32_e32 v114, 2, v99
	v_cmp_ge_i32_e64 s[4:5], v101, v103
	v_cndmask_b32_e64 v116, v20, v98, s[6:7]
	s_cbranch_vccz .LBB0_626
	s_lshl_b32 s6, s64, 7
	s_mul_i32 s7, s64, 0x4200
	s_add_i32 s7, s7, 0
	s_lshl_b32 s6, s6, 2
	s_add_i32 s7, s7, 0x10000
	v_lshlrev_b32_e32 v20, 2, v116
	s_add_i32 s8, s6, 0
	v_add3_u32 v20, s7, v20, v114
	s_add_i32 s8, s8, 0x20800
	v_lshlrev_b32_e32 v152, 2, v101
	v_add_u32_e32 v153, s8, v152
	v_add_u32_e32 v152, s46, v152
	ds_read_b128 v[120:123], v153
	ds_read_b128 v[124:127], v152
	ds_read_b128 v[128:131], v153 offset:32
	ds_read_b128 v[132:135], v152 offset:32
	ds_read_b128 v[136:139], v153 offset:64
	ds_read_b128 v[140:143], v152 offset:64
	ds_read_b128 v[144:147], v153 offset:96
	ds_read_b128 v[148:151], v152 offset:96
	s_and_saveexec_b64 s[6:7], s[4:5]
	s_cbranch_execz .LBB0_619
	v_lshlrev_b32_e32 v21, 2, v101
	v_add_u32_e32 v98, s8, v21
	v_add_u32_e32 v99, s46, v21
	s_waitcnt lgkmcnt(6)
	v_mov_b64_e32 v[104:105], v[120:121]
	v_mov_b64_e32 v[106:107], v[122:123]
	v_mov_b64_e32 v[108:109], v[124:125]
	v_mov_b64_e32 v[110:111], v[126:127]
	v_cmp_gt_i32_e32 vcc, v101, v100
	v_add_u32_e32 v21, v20, v21
	v_mul_f32_e32 v98, v2, v104
	v_sub_f32_e32 v99, v108, v117
	v_mul_f32_e32 v99, 0x3fb8aa3b, v99
	v_exp_f32_e32 v99, v99
	v_sub_f32_e32 v104, v109, v117
	v_mul_f32_e32 v104, 0x3fb8aa3b, v104
	v_exp_f32_e32 v108, v104
	v_mul_f32_e32 v98, v98, v99
	v_cndmask_b32_e32 v104, 0, v98, vcc
	v_mul_f32_e32 v98, v3, v105
	v_mul_f32_e32 v98, v98, v108
	v_cmp_ge_i32_e32 vcc, v101, v100
	v_sub_f32_e32 v99, v111, v117
	v_mul_f32_e32 v99, 0x3fb8aa3b, v99
	v_cndmask_b32_e32 v105, 0, v98, vcc
	v_sub_f32_e32 v98, v110, v117
	v_mul_f32_e32 v98, 0x3fb8aa3b, v98
	v_exp_f32_e32 v98, v98
	v_exp_f32_e32 v99, v99
	v_or_b32_e32 v108, 3, v101
	v_pk_mul_f32 v[106:107], v[4:5], v[106:107]
	v_or_b32_e32 v109, 2, v101
	v_pk_mul_f32 v[98:99], v[106:107], v[98:99]
	v_cmp_gt_i32_e32 vcc, v108, v100
	s_nop 1
	v_cndmask_b32_e32 v107, 0, v99, vcc
	v_cmp_gt_i32_e32 vcc, v109, v100
	s_nop 1
	v_cndmask_b32_e32 v106, 0, v98, vcc
	ds_write_b128 v21, v[104:107]
.LBB0_619:
	s_or_b64 exec, exec, s[6:7]
	v_add_u32_e32 v21, 8, v101
	v_cmp_ge_i32_e32 vcc, v21, v103
	s_and_saveexec_b64 s[4:5], vcc
	s_cbranch_execz .LBB0_621
	v_lshlrev_b32_e32 v112, 2, v101
	v_add_u32_e32 v98, s8, v112
	v_add_u32_e32 v99, s46, v112
	s_waitcnt lgkmcnt(4)
	v_mov_b64_e32 v[104:105], v[128:129]
	v_mov_b64_e32 v[106:107], v[130:131]
	v_mov_b64_e32 v[108:109], v[132:133]
	v_mov_b64_e32 v[110:111], v[134:135]
	v_cmp_gt_i32_e32 vcc, v21, v100
	v_mul_f32_e32 v98, v6, v104
	v_sub_f32_e32 v99, v108, v117
	v_mul_f32_e32 v99, 0x3fb8aa3b, v99
	v_exp_f32_e32 v99, v99
	v_sub_f32_e32 v104, v109, v117
	v_mul_f32_e32 v104, 0x3fb8aa3b, v104
	v_exp_f32_e32 v108, v104
	v_mul_f32_e32 v98, v98, v99
	v_cndmask_b32_e32 v104, 0, v98, vcc
	v_mul_f32_e32 v98, v7, v105
	v_mul_f32_e32 v98, v98, v108
	v_cmp_ge_i32_e32 vcc, v21, v100
	v_sub_f32_e32 v99, v111, v117
	v_mul_f32_e32 v99, 0x3fb8aa3b, v99
	v_cndmask_b32_e32 v105, 0, v98, vcc
	v_sub_f32_e32 v98, v110, v117
	v_mul_f32_e32 v98, 0x3fb8aa3b, v98
	v_exp_f32_e32 v98, v98
	v_exp_f32_e32 v99, v99
	v_or_b32_e32 v108, 3, v21
	v_pk_mul_f32 v[106:107], v[8:9], v[106:107]
	v_or_b32_e32 v21, 2, v21
	v_pk_mul_f32 v[98:99], v[106:107], v[98:99]
	v_cmp_gt_i32_e32 vcc, v108, v100
	s_nop 1
	v_cndmask_b32_e32 v107, 0, v99, vcc
	v_cmp_gt_i32_e32 vcc, v21, v100
	v_add_u32_e32 v21, v20, v112
	s_nop 0
	v_cndmask_b32_e32 v106, 0, v98, vcc
	ds_write_b128 v21, v[104:107] offset:32
.LBB0_621:
	s_or_b64 exec, exec, s[4:5]
	v_add_u32_e32 v21, 16, v101
	v_cmp_ge_i32_e32 vcc, v21, v103
	s_and_saveexec_b64 s[4:5], vcc
	s_cbranch_execz .LBB0_623
	v_lshlrev_b32_e32 v112, 2, v101
	v_add_u32_e32 v98, s8, v112
	v_add_u32_e32 v99, s46, v112
	s_waitcnt lgkmcnt(2)
	v_mov_b64_e32 v[104:105], v[136:137]
	v_mov_b64_e32 v[106:107], v[138:139]
	v_mov_b64_e32 v[108:109], v[140:141]
	v_mov_b64_e32 v[110:111], v[142:143]
	v_cmp_gt_i32_e32 vcc, v21, v100
	v_mul_f32_e32 v98, v10, v104
	v_sub_f32_e32 v99, v108, v117
	v_mul_f32_e32 v99, 0x3fb8aa3b, v99
	v_exp_f32_e32 v99, v99
	v_sub_f32_e32 v104, v109, v117
	v_mul_f32_e32 v104, 0x3fb8aa3b, v104
	v_exp_f32_e32 v108, v104
	v_mul_f32_e32 v98, v98, v99
	v_cndmask_b32_e32 v104, 0, v98, vcc
	v_mul_f32_e32 v98, v11, v105
	v_mul_f32_e32 v98, v98, v108
	v_cmp_ge_i32_e32 vcc, v21, v100
	v_sub_f32_e32 v99, v111, v117
	v_mul_f32_e32 v99, 0x3fb8aa3b, v99
	v_cndmask_b32_e32 v105, 0, v98, vcc
	v_sub_f32_e32 v98, v110, v117
	v_mul_f32_e32 v98, 0x3fb8aa3b, v98
	v_exp_f32_e32 v98, v98
	v_exp_f32_e32 v99, v99
	v_or_b32_e32 v108, 3, v21
	v_pk_mul_f32 v[106:107], v[12:13], v[106:107]
	v_or_b32_e32 v21, 2, v21
	v_pk_mul_f32 v[98:99], v[106:107], v[98:99]
	v_cmp_gt_i32_e32 vcc, v108, v100
	s_nop 1
	v_cndmask_b32_e32 v107, 0, v99, vcc
	v_cmp_gt_i32_e32 vcc, v21, v100
	v_add_u32_e32 v21, v20, v112
	s_nop 0
	v_cndmask_b32_e32 v106, 0, v98, vcc
	ds_write_b128 v21, v[104:107] offset:64
.LBB0_623:
	s_or_b64 exec, exec, s[4:5]
	v_add_u32_e32 v21, 24, v101
	v_cmp_ge_i32_e32 vcc, v21, v103
	s_and_saveexec_b64 s[4:5], vcc
	s_cbranch_execz .LBB0_625
	v_lshlrev_b32_e32 v112, 2, v101
	v_add_u32_e32 v98, s8, v112
	v_add_u32_e32 v99, s46, v112
	s_waitcnt lgkmcnt(0)
	v_mov_b64_e32 v[104:105], v[144:145]
	v_mov_b64_e32 v[106:107], v[146:147]
	v_mov_b64_e32 v[108:109], v[148:149]
	v_mov_b64_e32 v[110:111], v[150:151]
	v_cmp_gt_i32_e32 vcc, v21, v100
	v_add_u32_e32 v20, v20, v112
	v_mul_f32_e32 v98, v14, v104
	v_sub_f32_e32 v99, v108, v117
	v_mul_f32_e32 v99, 0x3fb8aa3b, v99
	v_exp_f32_e32 v99, v99
	v_sub_f32_e32 v104, v109, v117
	v_mul_f32_e32 v104, 0x3fb8aa3b, v104
	v_exp_f32_e32 v108, v104
	v_mul_f32_e32 v98, v98, v99
	v_cndmask_b32_e32 v104, 0, v98, vcc
	v_mul_f32_e32 v98, v15, v105
	v_mul_f32_e32 v98, v98, v108
	v_cmp_ge_i32_e32 vcc, v21, v100
	v_sub_f32_e32 v99, v111, v117
	v_mul_f32_e32 v99, 0x3fb8aa3b, v99
	v_cndmask_b32_e32 v105, 0, v98, vcc
	v_sub_f32_e32 v98, v110, v117
	v_mul_f32_e32 v98, 0x3fb8aa3b, v98
	v_exp_f32_e32 v98, v98
	v_exp_f32_e32 v99, v99
	v_or_b32_e32 v108, 3, v21
	v_pk_mul_f32 v[106:107], v[16:17], v[106:107]
	v_or_b32_e32 v21, 2, v21
	v_pk_mul_f32 v[98:99], v[106:107], v[98:99]
	v_cmp_gt_i32_e32 vcc, v108, v100
	s_nop 1
	v_cndmask_b32_e32 v107, 0, v99, vcc
	v_cmp_gt_i32_e32 vcc, v21, v100
	s_nop 1
	v_cndmask_b32_e32 v106, 0, v98, vcc
	ds_write_b128 v20, v[104:107] offset:96

.LBB0_628:
	s_lshl_b32 s4, s64, 1
	s_or_b32 s7, s4, 1
	s_lshl_b32 s4, s7, 8
	s_add_i32 s6, s4, 0
	s_add_i32 s6, s6, 0x21000
	s_add_i32 s4, s6, s40
	v_lshl_add_u32 v102, v102, 2, s4
	ds_read_b32 v102, v102
	v_readlane_b32 s4, v249, 58
	v_readlane_b32 s5, v249, 59
	s_andn2_b64 vcc, exec, s[4:5]
	s_mov_b64 s[4:5], -1
	s_mov_b32 s16, s47
	s_mov_b32 s17, 0x24300000
	s_cbranch_vccnz .LBB0_638
	s_lshl_b32 s4, s7, 6
	s_mulk_i32 s7, 0x2100
	s_add_i32 s5, s7, 0
	s_lshl_b32 s4, s4, 2
	s_add_i32 s5, s5, 0x10000
	v_lshlrev_b32_e32 v116, 2, v116
	s_add_i32 s4, s4, 0
	v_add3_u32 v114, s5, v116, v114
	s_add_i32 s4, s4, 0x20800
	v_lshlrev_b32_e32 v118, 2, v101
	v_cmp_ge_i32_e32 vcc, v101, v103
	s_waitcnt lgkmcnt(1)
	v_add_u32_e32 v117, s4, v118
	v_add_u32_e32 v116, s6, v118
	v_add_u32_e32 v114, v114, v118
	ds_read_b128 v[126:129], v117
	ds_read_b128 v[130:133], v116
	ds_read_b128 v[134:137], v117 offset:32
	ds_read_b128 v[138:141], v116 offset:32
	ds_read_b128 v[142:145], v117 offset:64
	ds_read_b128 v[146:149], v116 offset:64
	ds_read_b128 v[150:153], v117 offset:96
	ds_read_b128 v[154:157], v116 offset:96
	s_and_saveexec_b64 s[4:5], vcc
	s_cbranch_execz .LBB0_633
	s_waitcnt lgkmcnt(6)
	v_mov_b64_e32 v[118:119], v[126:127]
	v_mov_b64_e32 v[120:121], v[128:129]
	v_mov_b64_e32 v[122:123], v[130:131]
	v_mov_b64_e32 v[124:125], v[132:133]
	v_cmp_gt_i32_e32 vcc, v101, v100
	v_mul_f32_e32 v118, v2, v118
	v_sub_f32_e32 v122, v122, v102
	v_sub_f32_e32 v123, v123, v102
	v_mul_f32_e32 v122, 0x3fb8aa3b, v122
	v_mul_f32_e32 v123, 0x3fb8aa3b, v123
	v_exp_f32_e32 v122, v122
	v_exp_f32_e32 v123, v123
	v_mul_f32_e32 v119, v3, v119
	v_pk_mul_f32 v[120:121], v[4:5], v[120:121]
	v_mul_f32_e32 v118, v118, v122
	v_mul_f32_e32 v119, v119, v123
	v_sub_f32_e32 v122, v124, v102
	v_sub_f32_e32 v123, v125, v102
	v_mul_f32_e32 v122, 0x3fb8aa3b, v122
	v_mul_f32_e32 v123, 0x3fb8aa3b, v123
	v_exp_f32_e32 v122, v122
	v_exp_f32_e32 v123, v123
	v_cndmask_b32_e32 v118, 0, v118, vcc
	v_cmp_ge_i32_e32 vcc, v101, v100
	v_pk_mul_f32 v[120:121], v[120:121], v[122:123]
	s_nop 0
	v_cndmask_b32_e32 v119, 0, v119, vcc
	v_cmp_gt_i32_e32 vcc, v115, v100
	s_nop 1
	v_cndmask_b32_e32 v121, 0, v121, vcc
	v_cmp_gt_i32_e32 vcc, v113, v100
	s_nop 1
	v_cndmask_b32_e32 v120, 0, v120, vcc
	ds_write_b128 v114, v[118:121]
	s_or_b64 exec, exec, s[4:5]
	v_cmp_ge_i32_e32 vcc, v112, v103
	s_and_saveexec_b64 s[4:5], vcc
	s_cbranch_execnz .LBB0_634

.LBB0_632:
	s_waitcnt lgkmcnt(2)
	v_mov_b64_e32 v[118:119], v[142:143]
	v_mov_b64_e32 v[120:121], v[144:145]
	v_mov_b64_e32 v[122:123], v[146:147]
	v_mov_b64_e32 v[124:125], v[148:149]
	v_cmp_gt_i32_e32 vcc, v107, v100
	v_mul_f32_e32 v118, v10, v118
	v_sub_f32_e32 v122, v122, v102
	v_sub_f32_e32 v123, v123, v102
	v_mul_f32_e32 v122, 0x3fb8aa3b, v122
	v_mul_f32_e32 v123, 0x3fb8aa3b, v123
	v_exp_f32_e32 v122, v122
	v_exp_f32_e32 v123, v123
	v_mul_f32_e32 v119, v11, v119
	v_pk_mul_f32 v[120:121], v[12:13], v[120:121]
	v_mul_f32_e32 v118, v118, v122
	v_mul_f32_e32 v119, v119, v123
	v_sub_f32_e32 v122, v124, v102
	v_sub_f32_e32 v123, v125, v102
	v_mul_f32_e32 v122, 0x3fb8aa3b, v122
	v_mul_f32_e32 v123, 0x3fb8aa3b, v123
	v_exp_f32_e32 v122, v122
	v_exp_f32_e32 v123, v123
	v_cndmask_b32_e32 v118, 0, v118, vcc
	v_cmp_ge_i32_e32 vcc, v107, v100
	v_pk_mul_f32 v[120:121], v[120:121], v[122:123]
	s_nop 0
	v_cndmask_b32_e32 v119, 0, v119, vcc
	v_cmp_gt_i32_e32 vcc, v109, v100
	s_nop 1
	v_cndmask_b32_e32 v121, 0, v121, vcc
	v_cmp_gt_i32_e32 vcc, v108, v100
	s_nop 1
	v_cndmask_b32_e32 v120, 0, v120, vcc
	ds_write_b128 v114, v[118:121] offset:64
	s_or_b64 exec, exec, s[4:5]
	v_cmp_ge_i32_e32 vcc, v104, v103
	s_and_saveexec_b64 s[4:5], vcc
	s_cbranch_execnz .LBB0_636
	s_branch .LBB0_637

.LBB0_634:
	s_waitcnt lgkmcnt(4)
	v_mov_b64_e32 v[118:119], v[134:135]
	v_mov_b64_e32 v[120:121], v[136:137]
	v_mov_b64_e32 v[122:123], v[138:139]
	v_mov_b64_e32 v[124:125], v[140:141]
	v_cmp_gt_i32_e32 vcc, v112, v100
	v_mul_f32_e32 v118, v6, v118
	v_sub_f32_e32 v122, v122, v102
	v_sub_f32_e32 v123, v123, v102
	v_mul_f32_e32 v122, 0x3fb8aa3b, v122
	v_mul_f32_e32 v123, 0x3fb8aa3b, v123
	v_exp_f32_e32 v122, v122
	v_exp_f32_e32 v123, v123
	v_mul_f32_e32 v119, v7, v119
	v_pk_mul_f32 v[120:121], v[8:9], v[120:121]
	v_mul_f32_e32 v118, v118, v122
	v_mul_f32_e32 v119, v119, v123
	v_sub_f32_e32 v122, v124, v102
	v_sub_f32_e32 v123, v125, v102
	v_mul_f32_e32 v122, 0x3fb8aa3b, v122
	v_mul_f32_e32 v123, 0x3fb8aa3b, v123
	v_exp_f32_e32 v122, v122
	v_exp_f32_e32 v123, v123
	v_cndmask_b32_e32 v118, 0, v118, vcc
	v_cmp_ge_i32_e32 vcc, v112, v100
	v_pk_mul_f32 v[120:121], v[120:121], v[122:123]
	s_nop 0
	v_cndmask_b32_e32 v119, 0, v119, vcc
	v_cmp_gt_i32_e32 vcc, v111, v100
	s_nop 1
	v_cndmask_b32_e32 v121, 0, v121, vcc
	v_cmp_gt_i32_e32 vcc, v110, v100
	s_nop 1
	v_cndmask_b32_e32 v120, 0, v120, vcc
	ds_write_b128 v114, v[118:121] offset:32
	s_or_b64 exec, exec, s[4:5]
	v_cmp_ge_i32_e32 vcc, v107, v103
	s_and_saveexec_b64 s[4:5], vcc
	s_cbranch_execnz .LBB0_632

.LBB0_636:
	s_waitcnt lgkmcnt(0)
	v_mov_b64_e32 v[118:119], v[150:151]
	v_mov_b64_e32 v[120:121], v[152:153]
	v_mov_b64_e32 v[122:123], v[154:155]
	v_mov_b64_e32 v[124:125], v[156:157]
	v_cmp_gt_i32_e32 vcc, v104, v100
	v_mul_f32_e32 v103, v14, v118
	v_sub_f32_e32 v116, v122, v102
	v_mul_f32_e32 v116, 0x3fb8aa3b, v116
	v_sub_f32_e32 v118, v123, v102
	v_exp_f32_e32 v116, v116
	v_mul_f32_e32 v118, 0x3fb8aa3b, v118
	v_exp_f32_e32 v118, v118
	v_mul_f32_e32 v117, v15, v119
	v_mul_f32_e32 v103, v103, v116
	v_cndmask_b32_e32 v116, 0, v103, vcc
	v_mul_f32_e32 v103, v117, v118
	v_sub_f32_e32 v117, v124, v102
	v_mul_f32_e32 v117, 0x3fb8aa3b, v117
	v_exp_f32_e32 v118, v117
	v_sub_f32_e32 v117, v125, v102
	v_mul_f32_e32 v117, 0x3fb8aa3b, v117
	v_exp_f32_e32 v119, v117
	v_cmp_ge_i32_e32 vcc, v104, v100
	v_pk_mul_f32 v[120:121], v[16:17], v[120:121]
	s_nop 0
	v_cndmask_b32_e32 v117, 0, v103, vcc
	v_pk_mul_f32 v[118:119], v[120:121], v[118:119]
	v_cmp_gt_i32_e32 vcc, v106, v100
	s_nop 1
	v_cndmask_b32_e32 v119, 0, v119, vcc
	v_cmp_gt_i32_e32 vcc, v105, v100
	s_nop 1
	v_cndmask_b32_e32 v118, 0, v118, vcc
	ds_write_b128 v114, v[116:119] offset:96
